# P1 slack conversion: converted-weight stores marked nt (streamed; they are first read two phases later) to keep them out of the GEMM workgroups' L2 working set
# baseline (speedup 1.0000x reference)
; __device__ __forceinline__ void tr_item(const float* W, int N, int k0, int n0, bf16* WT, int dst_pitch, int dst_row0, int dst_k0, int ncopies, int copy_stride, LAS float* scr, int lane) {
; #pragma unroll 8
;     for (int i = 0; i < 32; ++i) { const int kk = 2 * i + (lane >> 5); scr[kk * 33 + (lane & 31)] = __builtin_nontemporal_load(W + (size_t)(k0 + kk) * N + n0 + (lane & 31)); }
.LBB0_190:
	v_add_u32_e32 v30, s53, v19
	v_add_u32_e32 v31, 6, v30
	v_add_u32_e32 v32, 8, v30
	v_add_u32_e32 v34, 10, v30
	v_add_u32_e32 v50, 12, v30
	v_add_u32_e32 v52, 14, v30
	v_mad_i64_i32 v[30:31], s[54:55], v31, s49, v[20:21]
	v_mad_i64_i32 v[32:33], s[54:55], v32, s49, v[20:21]
	v_mad_i64_i32 v[34:35], s[54:55], v34, s49, v[20:21]
	global_load_dword v176, v[26:27], off nt
	global_load_dword v177, v[24:25], off nt
	global_load_dword v178, v[22:23], off nt
	v_mad_i64_i32 v[50:51], s[54:55], v50, s49, v[20:21]
	v_mad_i64_i32 v[52:53], s[54:55], v52, s49, v[20:21]
	global_load_dword v179, v[30:31], off nt
	global_load_dword v180, v[32:33], off nt
	global_load_dword v181, v[34:35], off nt
	global_load_dword v182, v[50:51], off nt
	global_load_dword v183, v[52:53], off nt
	s_add_i32 s53, s53, 16
	v_lshl_add_u64 v[22:23], v[22:23], 0, s[6:7]
	v_lshl_add_u64 v[24:25], v[24:25], 0, s[6:7]
	v_lshl_add_u64 v[26:27], v[26:27], 0, s[6:7]
	v_add_u32_e32 v30, s53, v19
	v_add_u32_e32 v31, 6, v30
	v_add_u32_e32 v32, 8, v30
	v_add_u32_e32 v34, 10, v30
	v_add_u32_e32 v50, 12, v30
	v_add_u32_e32 v52, 14, v30
	v_mad_i64_i32 v[30:31], s[54:55], v31, s49, v[20:21]
	v_mad_i64_i32 v[32:33], s[54:55], v32, s49, v[20:21]
	v_mad_i64_i32 v[34:35], s[54:55], v34, s49, v[20:21]
	global_load_dword v184, v[26:27], off nt
	global_load_dword v185, v[24:25], off nt
	global_load_dword v186, v[22:23], off nt
	v_mad_i64_i32 v[50:51], s[54:55], v50, s49, v[20:21]
	v_mad_i64_i32 v[52:53], s[54:55], v52, s49, v[20:21]
	global_load_dword v187, v[30:31], off nt
	global_load_dword v188, v[32:33], off nt
	global_load_dword v189, v[34:35], off nt
	global_load_dword v190, v[50:51], off nt
	global_load_dword v191, v[52:53], off nt
	s_add_i32 s53, s53, 16
	v_lshl_add_u64 v[22:23], v[22:23], 0, s[6:7]
	v_lshl_add_u64 v[24:25], v[24:25], 0, s[6:7]
	v_lshl_add_u64 v[26:27], v[26:27], 0, s[6:7]
	v_add_u32_e32 v30, s53, v19
	v_add_u32_e32 v31, 6, v30
	v_add_u32_e32 v32, 8, v30
	v_add_u32_e32 v34, 10, v30
	v_add_u32_e32 v50, 12, v30
	v_add_u32_e32 v52, 14, v30
	v_mad_i64_i32 v[30:31], s[54:55], v31, s49, v[20:21]
	v_mad_i64_i32 v[32:33], s[54:55], v32, s49, v[20:21]
	v_mad_i64_i32 v[34:35], s[54:55], v34, s49, v[20:21]
	global_load_dword v192, v[26:27], off nt
	global_load_dword v193, v[24:25], off nt
	global_load_dword v194, v[22:23], off nt
	v_mad_i64_i32 v[50:51], s[54:55], v50, s49, v[20:21]
	v_mad_i64_i32 v[52:53], s[54:55], v52, s49, v[20:21]
	global_load_dword v195, v[30:31], off nt
	global_load_dword v196, v[32:33], off nt
	global_load_dword v197, v[34:35], off nt
	global_load_dword v198, v[50:51], off nt
	global_load_dword v199, v[52:53], off nt
	s_add_i32 s53, s53, 16
	v_lshl_add_u64 v[22:23], v[22:23], 0, s[6:7]
	v_lshl_add_u64 v[24:25], v[24:25], 0, s[6:7]
	v_lshl_add_u64 v[26:27], v[26:27], 0, s[6:7]
	v_add_u32_e32 v30, s53, v19
	v_add_u32_e32 v31, 6, v30
	v_add_u32_e32 v32, 8, v30
	v_add_u32_e32 v34, 10, v30
	v_add_u32_e32 v50, 12, v30
	v_add_u32_e32 v52, 14, v30
	v_mad_i64_i32 v[30:31], s[54:55], v31, s49, v[20:21]
	v_mad_i64_i32 v[32:33], s[54:55], v32, s49, v[20:21]
	v_mad_i64_i32 v[34:35], s[54:55], v34, s49, v[20:21]
	global_load_dword v200, v[26:27], off nt
	global_load_dword v201, v[24:25], off nt
	global_load_dword v202, v[22:23], off nt
	v_mad_i64_i32 v[50:51], s[54:55], v50, s49, v[20:21]
	v_mad_i64_i32 v[52:53], s[54:55], v52, s49, v[20:21]
	global_load_dword v203, v[30:31], off nt
	global_load_dword v204, v[32:33], off nt
	global_load_dword v205, v[34:35], off nt
	global_load_dword v206, v[50:51], off nt
	global_load_dword v207, v[52:53], off nt
	s_add_i32 s53, s53, 16
	v_lshl_add_u64 v[22:23], v[22:23], 0, s[6:7]
	v_lshl_add_u64 v[24:25], v[24:25], 0, s[6:7]
	v_lshl_add_u64 v[26:27], v[26:27], 0, s[6:7]
	s_waitcnt vmcnt(24)
; #define LAS __attribute__((address_space(3)))
; __device__ __forceinline__ unsigned cvtpk(float lo, float hi) { f32x2_t v = {lo, hi}; bf16x2_t b = __builtin_convertvector(v, bf16x2_t); return __builtin_bit_cast(unsigned, b); }
; __device__ __forceinline__ void tr_item(const float* W, int N, int k0, int n0, bf16* WT, int dst_pitch, int dst_row0, int dst_k0, int ncopies, int copy_stride, LAS float* scr, int lane) {
;     ...
;     for (int i = 0; i < 32; ++i) { const int kk = 2 * i + (lane >> 5); scr[kk * 33 + (lane & 31)] = __builtin_nontemporal_load(W + (size_t)(k0 + kk) * N + n0 + (lane & 31)); }
;     asm volatile("s_waitcnt lgkmcnt(0)" ::: "memory");
;     const int c = lane & 7;
; #pragma unroll
;     for (int j = 0; j < 4; ++j) { const int n = (lane >> 3) + 8 * j; const LAS float* s = scr + (8 * c) * 33 + n;
;         u32x4 o; o.x = cvtpk(s[0 * 33], s[1 * 33]); o.y = cvtpk(s[2 * 33], s[3 * 33]); o.z = cvtpk(s[4 * 33], s[5 * 33]); o.w = cvtpk(s[6 * 33], s[7 * 33]);
;         bf16* dst = WT + (size_t)(dst_row0 + n0 + n) * dst_pitch + dst_k0 + k0 + 8 * c;
;         for (int cp = 0; cp < ncopies; ++cp) *(u32x4*)(dst + (size_t)cp * copy_stride) = o; }
;     asm volatile("s_waitcnt lgkmcnt(0)" ::: "memory");
	v_add_u32_e32 v35, 0x400, v28
	ds_write2_b32 v28, v176, v177 offset1:66
	ds_write2_b32 v28, v178, v179 offset0:132 offset1:198
	ds_write2_b32 v35, v180, v181 offset0:8 offset1:74
	ds_write2_b32 v35, v182, v183 offset0:140 offset1:206
	v_add_u32_e32 v28, 0x840, v28
	s_waitcnt vmcnt(16)
	v_add_u32_e32 v35, 0x400, v28
	ds_write2_b32 v28, v184, v185 offset1:66
	ds_write2_b32 v28, v186, v187 offset0:132 offset1:198
	ds_write2_b32 v35, v188, v189 offset0:8 offset1:74
	ds_write2_b32 v35, v190, v191 offset0:140 offset1:206
	v_add_u32_e32 v28, 0x840, v28
	s_waitcnt vmcnt(8)
	v_add_u32_e32 v35, 0x400, v28
	ds_write2_b32 v28, v192, v193 offset1:66
	ds_write2_b32 v28, v194, v195 offset0:132 offset1:198
	ds_write2_b32 v35, v196, v197 offset0:8 offset1:74
	ds_write2_b32 v35, v198, v199 offset0:140 offset1:206
	v_add_u32_e32 v28, 0x840, v28
	s_waitcnt vmcnt(0)
	v_add_u32_e32 v35, 0x400, v28
	ds_write2_b32 v28, v200, v201 offset1:66
	ds_write2_b32 v28, v202, v203 offset0:132 offset1:198
	ds_write2_b32 v35, v204, v205 offset0:8 offset1:74
	ds_write2_b32 v35, v206, v207 offset0:140 offset1:206
	v_add_u32_e32 v28, 0x840, v28
	s_lshl_b32 s21, s52, 6
	s_and_b64 s[22:23], s[22:23], exec
	s_cselect_b32 s22, 0x80, 0
	s_and_b32 s21, s21, 0x1f00
	s_waitcnt lgkmcnt(0)
	s_and_b32 s4, s4, 0x60
	s_or_b32 s21, s21, s22
	ds_read2_b32 v[24:25], v37 offset0:33 offset1:41
	ds_read2_b32 v[26:27], v37 offset1:8
	ds_read2_b32 v[28:29], v37 offset0:66 offset1:74
	ds_read2_b32 v[30:31], v37 offset0:99 offset1:107
	ds_read2_b32 v[32:33], v37 offset0:132 offset1:140
	ds_read2_b32 v[34:35], v37 offset0:165 offset1:173
	ds_read2_b32 v[50:51], v37 offset0:198 offset1:206
	ds_read2_b32 v[52:53], v37 offset0:231 offset1:239
	s_or_b32 s4, s21, s4
	v_add_u32_e32 v56, s4, v36
	s_mov_b32 s21, s5
	v_ashrrev_i32_e32 v57, 31, v56
	v_lshl_add_u64 v[54:55], s[20:21], 1, v[4:5]
	v_lshlrev_b64 v[56:57], 11, v[56:57]
	s_waitcnt lgkmcnt(6)
	v_cvt_pk_bf16_f32 v20, v26, v24
	s_waitcnt lgkmcnt(4)
	v_cvt_pk_bf16_f32 v21, v28, v30
	s_waitcnt lgkmcnt(2)
	v_cvt_pk_bf16_f32 v22, v32, v34
	s_waitcnt lgkmcnt(0)
	v_cvt_pk_bf16_f32 v23, v50, v52
	v_lshl_add_u64 v[56:57], v[54:55], 0, v[56:57]
	v_add_u32_e32 v24, s4, v38
	global_store_dwordx4 v[56:57], v[20:23], off nt
	s_mov_b64 s[20:21], 0
	s_nop 0
	v_cvt_pk_bf16_f32 v20, v27, v25
	v_ashrrev_i32_e32 v25, 31, v24
	v_cvt_pk_bf16_f32 v21, v29, v31
	v_cvt_pk_bf16_f32 v22, v33, v35
	v_cvt_pk_bf16_f32 v23, v51, v53
	v_lshlrev_b64 v[24:25], 11, v[24:25]
	ds_read2_b32 v[26:27], v37 offset0:49 offset1:57
	ds_read2_b32 v[28:29], v37 offset0:16 offset1:24
	ds_read2_b32 v[30:31], v37 offset0:82 offset1:90
	ds_read2_b32 v[32:33], v37 offset0:115 offset1:123
	ds_read2_b32 v[34:35], v37 offset0:148 offset1:156
	ds_read2_b32 v[50:51], v37 offset0:181 offset1:189
	ds_read2_b32 v[52:53], v37 offset0:214 offset1:222
	ds_read2_b32 v[56:57], v37 offset0:247 offset1:255
	v_lshl_add_u64 v[24:25], v[54:55], 0, v[24:25]
	global_store_dwordx4 v[24:25], v[20:23], off nt
	v_add_u32_e32 v24, s4, v39
	v_ashrrev_i32_e32 v25, 31, v24
	v_lshlrev_b64 v[24:25], 11, v[24:25]
	s_waitcnt lgkmcnt(6)
	v_cvt_pk_bf16_f32 v20, v28, v26
	s_waitcnt lgkmcnt(4)
	v_cvt_pk_bf16_f32 v21, v30, v32
	s_waitcnt lgkmcnt(2)
	v_cvt_pk_bf16_f32 v22, v34, v50
	s_waitcnt lgkmcnt(0)
	v_cvt_pk_bf16_f32 v23, v52, v56
	v_lshl_add_u64 v[24:25], v[54:55], 0, v[24:25]
	global_store_dwordx4 v[24:25], v[20:23], off nt
	v_add_u32_e32 v24, s4, v40
	v_ashrrev_i32_e32 v25, 31, v24
	v_lshlrev_b64 v[24:25], 11, v[24:25]
	v_cvt_pk_bf16_f32 v20, v29, v27
	v_cvt_pk_bf16_f32 v21, v31, v33
	v_cvt_pk_bf16_f32 v22, v35, v51
	v_cvt_pk_bf16_f32 v23, v53, v57
	v_lshl_add_u64 v[24:25], v[54:55], 0, v[24:25]
	global_store_dwordx4 v[24:25], v[20:23], off nt
	s_waitcnt lgkmcnt(0)

; #define LAS __attribute__((address_space(3)))
; __device__ __forceinline__ unsigned cvtpk(float lo, float hi) { f32x2_t v = {lo, hi}; bf16x2_t b = __builtin_convertvector(v, bf16x2_t); return __builtin_bit_cast(unsigned, b); }
; __device__ __forceinline__ void tr_item(const float* W, int N, int k0, int n0, bf16* WT, int dst_pitch, int dst_row0, int dst_k0, int ncopies, int copy_stride, LAS float* scr, int lane) {
; #pragma unroll 8
;     for (int i = 0; i < 32; ++i) { const int kk = 2 * i + (lane >> 5); scr[kk * 33 + (lane & 31)] = __builtin_nontemporal_load(W + (size_t)(k0 + kk) * N + n0 + (lane & 31)); }
;     asm volatile("s_waitcnt lgkmcnt(0)" ::: "memory");
;     const int c = lane & 7;
; #pragma unroll
;     for (int j = 0; j < 4; ++j) { const int n = (lane >> 3) + 8 * j; const LAS float* s = scr + (8 * c) * 33 + n;
;         u32x4 o; o.x = cvtpk(s[0 * 33], s[1 * 33]); o.y = cvtpk(s[2 * 33], s[3 * 33]); o.z = cvtpk(s[4 * 33], s[5 * 33]); o.w = cvtpk(s[6 * 33], s[7 * 33]);
;         bf16* dst = WT + (size_t)(dst_row0 + n0 + n) * dst_pitch + dst_k0 + k0 + 8 * c;
;         for (int cp = 0; cp < ncopies; ++cp) *(u32x4*)(dst + (size_t)cp * copy_stride) = o; }
;     asm volatile("s_waitcnt lgkmcnt(0)" ::: "memory");
.LBB0_194:
	v_add_u32_e32 v31, s4, v20
	v_add_u32_e32 v30, 6, v31
	v_add_u32_e32 v32, 8, v31
	v_add_u32_e32 v34, 10, v31
	v_add_u32_e32 v50, 12, v31
	v_add_u32_e32 v52, 14, v31
	v_ashrrev_i32_e32 v31, 31, v30
	v_ashrrev_i32_e32 v33, 31, v32
	v_ashrrev_i32_e32 v35, 31, v34
	v_ashrrev_i32_e32 v51, 31, v50
	v_ashrrev_i32_e32 v53, 31, v52
	v_lshlrev_b64 v[30:31], 12, v[30:31]
	v_lshlrev_b64 v[32:33], 12, v[32:33]
	v_lshlrev_b64 v[34:35], 12, v[34:35]
	v_lshlrev_b64 v[50:51], 12, v[50:51]
	v_lshlrev_b64 v[52:53], 12, v[52:53]
	v_lshl_add_u64 v[30:31], v[28:29], 0, v[30:31]
	v_lshl_add_u64 v[32:33], v[28:29], 0, v[32:33]
	v_lshl_add_u64 v[34:35], v[28:29], 0, v[34:35]
	global_load_dword v21, v[26:27], off nt
	global_load_dword v49, v[24:25], off nt
	global_load_dword v54, v[22:23], off nt
	v_lshl_add_u64 v[50:51], v[28:29], 0, v[50:51]
	v_lshl_add_u64 v[52:53], v[28:29], 0, v[52:53]
	global_load_dword v30, v[30:31], off nt
	s_nop 0
	global_load_dword v31, v[32:33], off nt
	s_nop 0
	global_load_dword v32, v[34:35], off nt
	global_load_dword v33, v[50:51], off nt
	s_nop 0
	global_load_dword v34, v[52:53], off nt
	s_add_i32 s4, s4, 16
	v_add_u32_e32 v35, 0x400, v19
	v_lshl_add_u64 v[22:23], v[22:23], 0, s[8:9]
	v_lshl_add_u64 v[24:25], v[24:25], 0, s[8:9]
	v_lshl_add_u64 v[26:27], v[26:27], 0, s[8:9]
	s_cmp_lg_u32 s4, 64
	s_waitcnt vmcnt(0)
	ds_write2_b32 v19, v21, v49 offset1:66
	ds_write2_b32 v19, v54, v30 offset0:132 offset1:198
	ds_write2_b32 v35, v31, v32 offset0:8 offset1:74
	ds_write2_b32 v35, v33, v34 offset0:140 offset1:206
	v_add_u32_e32 v19, 0x840, v19
	s_cbranch_scc1 .LBB0_194
	s_waitcnt lgkmcnt(0)
	s_lshl_b32 s4, s27, 1
	ds_read2_b32 v[24:25], v37 offset0:33 offset1:41
	ds_read2_b32 v[26:27], v37 offset1:8
	ds_read2_b32 v[28:29], v37 offset0:66 offset1:74
	ds_read2_b32 v[30:31], v37 offset0:99 offset1:107
	ds_read2_b32 v[32:33], v37 offset0:132 offset1:140
	ds_read2_b32 v[34:35], v37 offset0:165 offset1:173
	ds_read2_b32 v[50:51], v37 offset0:198 offset1:206
	ds_read2_b32 v[52:53], v37 offset0:231 offset1:239
	s_add_i32 s4, s4, 0x7fffee00
	s_and_b32 s4, s4, 0x7fffffc0
	v_add_u32_e32 v56, s20, v36
	s_lshl_b32 s4, s4, 1
	v_ashrrev_i32_e32 v57, 31, v56
	v_lshl_add_u64 v[54:55], v[10:11], 0, s[4:5]
	v_lshlrev_b64 v[56:57], 11, v[56:57]
	s_waitcnt lgkmcnt(6)
	v_cvt_pk_bf16_f32 v20, v26, v24
	s_waitcnt lgkmcnt(4)
	v_cvt_pk_bf16_f32 v21, v28, v30
	s_waitcnt lgkmcnt(2)
	v_cvt_pk_bf16_f32 v22, v32, v34
	s_waitcnt lgkmcnt(0)
	v_cvt_pk_bf16_f32 v23, v50, v52
	v_lshl_add_u64 v[56:57], v[54:55], 0, v[56:57]
	v_add_u32_e32 v24, s20, v38
	global_store_dwordx4 v[56:57], v[20:23], off nt
	s_nop 1
	v_cvt_pk_bf16_f32 v20, v27, v25
	v_ashrrev_i32_e32 v25, 31, v24
	v_cvt_pk_bf16_f32 v21, v29, v31
	v_cvt_pk_bf16_f32 v22, v33, v35
	v_cvt_pk_bf16_f32 v23, v51, v53
	v_lshlrev_b64 v[24:25], 11, v[24:25]
	ds_read2_b32 v[26:27], v37 offset0:49 offset1:57
	ds_read2_b32 v[28:29], v37 offset0:16 offset1:24
	ds_read2_b32 v[30:31], v37 offset0:82 offset1:90
	ds_read2_b32 v[32:33], v37 offset0:115 offset1:123
	ds_read2_b32 v[34:35], v37 offset0:148 offset1:156
	ds_read2_b32 v[50:51], v37 offset0:181 offset1:189
	ds_read2_b32 v[52:53], v37 offset0:214 offset1:222
	ds_read2_b32 v[56:57], v37 offset0:247 offset1:255
	v_lshl_add_u64 v[24:25], v[54:55], 0, v[24:25]
	global_store_dwordx4 v[24:25], v[20:23], off nt
	v_add_u32_e32 v24, s20, v39
	v_ashrrev_i32_e32 v25, 31, v24
	v_lshlrev_b64 v[24:25], 11, v[24:25]
	s_waitcnt lgkmcnt(6)
	v_cvt_pk_bf16_f32 v20, v28, v26
	s_waitcnt lgkmcnt(4)
	v_cvt_pk_bf16_f32 v21, v30, v32
	s_waitcnt lgkmcnt(2)
	v_cvt_pk_bf16_f32 v22, v34, v50
	s_waitcnt lgkmcnt(0)
	v_cvt_pk_bf16_f32 v23, v52, v56
	v_lshl_add_u64 v[24:25], v[54:55], 0, v[24:25]
	global_store_dwordx4 v[24:25], v[20:23], off nt
	v_add_u32_e32 v24, s20, v40
	v_ashrrev_i32_e32 v25, 31, v24
	v_lshlrev_b64 v[24:25], 11, v[24:25]
	v_cvt_pk_bf16_f32 v20, v29, v27
	v_cvt_pk_bf16_f32 v21, v31, v33
	v_cvt_pk_bf16_f32 v22, v35, v51
	v_cvt_pk_bf16_f32 v23, v53, v57
	v_lshl_add_u64 v[24:25], v[54:55], 0, v[24:25]
	global_store_dwordx4 v[24:25], v[20:23], off nt
	s_waitcnt lgkmcnt(0)

; #define LAS __attribute__((address_space(3)))
; __device__ __forceinline__ unsigned cvtpk(float lo, float hi) { f32x2_t v = {lo, hi}; bf16x2_t b = __builtin_convertvector(v, bf16x2_t); return __builtin_bit_cast(unsigned, b); }
; __device__ __forceinline__ void tr_item(const float* W, int N, int k0, int n0, bf16* WT, int dst_pitch, int dst_row0, int dst_k0, int ncopies, int copy_stride, LAS float* scr, int lane) {
; #pragma unroll 8
;     for (int i = 0; i < 32; ++i) { const int kk = 2 * i + (lane >> 5); scr[kk * 33 + (lane & 31)] = __builtin_nontemporal_load(W + (size_t)(k0 + kk) * N + n0 + (lane & 31)); }
;     asm volatile("s_waitcnt lgkmcnt(0)" ::: "memory");
;     const int c = lane & 7;
; #pragma unroll
;     for (int j = 0; j < 4; ++j) { const int n = (lane >> 3) + 8 * j; const LAS float* s = scr + (8 * c) * 33 + n;
;         u32x4 o; o.x = cvtpk(s[0 * 33], s[1 * 33]); o.y = cvtpk(s[2 * 33], s[3 * 33]); o.z = cvtpk(s[4 * 33], s[5 * 33]); o.w = cvtpk(s[6 * 33], s[7 * 33]);
;         bf16* dst = WT + (size_t)(dst_row0 + n0 + n) * dst_pitch + dst_k0 + k0 + 8 * c;
;         for (int cp = 0; cp < ncopies; ++cp) *(u32x4*)(dst + (size_t)cp * copy_stride) = o; }
;     asm volatile("s_waitcnt lgkmcnt(0)" ::: "memory");
.LBB0_199:
	v_lshl_add_u64 v[50:51], v[34:35], 0, s[20:21]
	v_lshl_add_u64 v[52:53], v[32:33], 0, s[20:21]
	v_lshl_add_u64 v[54:55], v[30:31], 0, s[20:21]
	v_lshl_add_u64 v[56:57], v[28:29], 0, s[20:21]
	v_lshl_add_u64 v[58:59], v[26:27], 0, s[20:21]
	v_lshl_add_u64 v[60:61], v[24:25], 0, s[20:21]
	v_lshl_add_u64 v[62:63], v[22:23], 0, s[20:21]
	v_lshl_add_u64 v[64:65], v[20:21], 0, s[20:21]
	global_load_dword v49, v[50:51], off nt
	s_nop 0
	global_load_dword v50, v[52:53], off nt
	global_load_dword v51, v[54:55], off nt
	s_nop 0
	global_load_dword v52, v[56:57], off nt
	global_load_dword v53, v[58:59], off nt
	global_load_dword v54, v[60:61], off nt
	global_load_dword v55, v[62:63], off nt
	s_nop 0
	global_load_dword v56, v[64:65], off nt
	s_add_u32 s20, s20, 0x10000
	s_addc_u32 s21, s21, 0
	v_add_u32_e32 v57, 0x400, v19
	s_cmp_lg_u32 s20, 0x40000
	s_waitcnt vmcnt(0)
	ds_write2_b32 v19, v49, v50 offset1:66
	ds_write2_b32 v19, v51, v52 offset0:132 offset1:198
	ds_write2_b32 v57, v53, v54 offset0:8 offset1:74
	ds_write2_b32 v57, v55, v56 offset0:140 offset1:206
	v_add_u32_e32 v19, 0x840, v19
	s_cbranch_scc1 .LBB0_199
	s_add_i32 s4, s27, 0xfffffa00
	s_lshr_b32 s4, s4, 8
	s_lshl_b32 s20, s27, 5
	s_and_b32 s22, s20, 0x3e0
	s_lshl_b64 s[20:21], s[4:5], 20
	s_add_u32 s4, s79, s20
	s_waitcnt lgkmcnt(0)
	s_addc_u32 s21, s81, s21
	s_lshl_b32 s20, s27, 2
	ds_read2_b32 v[24:25], v37 offset0:33 offset1:41
	ds_read2_b32 v[26:27], v37 offset1:8
	ds_read2_b32 v[28:29], v37 offset0:66 offset1:74
	ds_read2_b32 v[30:31], v37 offset0:99 offset1:107
	ds_read2_b32 v[32:33], v37 offset0:132 offset1:140
	ds_read2_b32 v[34:35], v37 offset0:165 offset1:173
	ds_read2_b32 v[50:51], v37 offset0:198 offset1:206
	ds_read2_b32 v[52:53], v37 offset0:231 offset1:239
	s_and_b32 s20, s20, 0x380
	s_add_u32 s20, s4, s20
	v_add_u32_e32 v56, s22, v36
	s_addc_u32 s21, s21, 0
	v_ashrrev_i32_e32 v57, 31, v56
	v_lshl_add_u64 v[54:55], s[20:21], 0, v[2:3]
	v_lshlrev_b64 v[56:57], 10, v[56:57]
	s_waitcnt lgkmcnt(6)
	v_cvt_pk_bf16_f32 v20, v26, v24
	s_waitcnt lgkmcnt(4)
	v_cvt_pk_bf16_f32 v21, v28, v30
	s_waitcnt lgkmcnt(2)
	v_cvt_pk_bf16_f32 v22, v32, v34
	s_waitcnt lgkmcnt(0)
	v_cvt_pk_bf16_f32 v23, v50, v52
	v_lshl_add_u64 v[56:57], v[54:55], 0, v[56:57]
	v_add_u32_e32 v24, s22, v38
	global_store_dwordx4 v[56:57], v[20:23], off nt
	s_nop 1
	v_cvt_pk_bf16_f32 v20, v27, v25
	v_ashrrev_i32_e32 v25, 31, v24
	v_cvt_pk_bf16_f32 v21, v29, v31
	v_cvt_pk_bf16_f32 v22, v33, v35
	v_cvt_pk_bf16_f32 v23, v51, v53
	v_lshlrev_b64 v[24:25], 10, v[24:25]
	ds_read2_b32 v[26:27], v37 offset0:49 offset1:57
	ds_read2_b32 v[28:29], v37 offset0:16 offset1:24
	ds_read2_b32 v[30:31], v37 offset0:82 offset1:90
	ds_read2_b32 v[32:33], v37 offset0:115 offset1:123
	ds_read2_b32 v[34:35], v37 offset0:148 offset1:156
	ds_read2_b32 v[50:51], v37 offset0:181 offset1:189
	ds_read2_b32 v[52:53], v37 offset0:214 offset1:222
	ds_read2_b32 v[56:57], v37 offset0:247 offset1:255
	v_lshl_add_u64 v[24:25], v[54:55], 0, v[24:25]
	global_store_dwordx4 v[24:25], v[20:23], off nt
	v_add_u32_e32 v24, s22, v39
	v_ashrrev_i32_e32 v25, 31, v24
	v_lshlrev_b64 v[24:25], 10, v[24:25]
	s_waitcnt lgkmcnt(6)
	v_cvt_pk_bf16_f32 v20, v28, v26
	s_waitcnt lgkmcnt(4)
	v_cvt_pk_bf16_f32 v21, v30, v32
	s_waitcnt lgkmcnt(2)
	v_cvt_pk_bf16_f32 v22, v34, v50
	s_waitcnt lgkmcnt(0)
	v_cvt_pk_bf16_f32 v23, v52, v56
	v_lshl_add_u64 v[24:25], v[54:55], 0, v[24:25]
	global_store_dwordx4 v[24:25], v[20:23], off nt
	v_add_u32_e32 v24, s22, v40
	v_ashrrev_i32_e32 v25, 31, v24
	v_lshlrev_b64 v[24:25], 10, v[24:25]
	v_cvt_pk_bf16_f32 v20, v29, v27
	v_cvt_pk_bf16_f32 v21, v31, v33
	v_cvt_pk_bf16_f32 v22, v35, v51
	v_cvt_pk_bf16_f32 v23, v53, v57
	v_lshl_add_u64 v[24:25], v[54:55], 0, v[24:25]
	global_store_dwordx4 v[24:25], v[20:23], off nt
	s_waitcnt lgkmcnt(0)

; #define LAS __attribute__((address_space(3)))
; __device__ __forceinline__ unsigned cvtpk(float lo, float hi) { f32x2_t v = {lo, hi}; bf16x2_t b = __builtin_convertvector(v, bf16x2_t); return __builtin_bit_cast(unsigned, b); }
; __device__ __forceinline__ void tr_item(const float* W, int N, int k0, int n0, bf16* WT, int dst_pitch, int dst_row0, int dst_k0, int ncopies, int copy_stride, LAS float* scr, int lane) {
; #pragma unroll 8
;     for (int i = 0; i < 32; ++i) { const int kk = 2 * i + (lane >> 5); scr[kk * 33 + (lane & 31)] = __builtin_nontemporal_load(W + (size_t)(k0 + kk) * N + n0 + (lane & 31)); }
;     asm volatile("s_waitcnt lgkmcnt(0)" ::: "memory");
;     const int c = lane & 7;
; #pragma unroll
;     for (int j = 0; j < 4; ++j) { const int n = (lane >> 3) + 8 * j; const LAS float* s = scr + (8 * c) * 33 + n;
;         u32x4 o; o.x = cvtpk(s[0 * 33], s[1 * 33]); o.y = cvtpk(s[2 * 33], s[3 * 33]); o.z = cvtpk(s[4 * 33], s[5 * 33]); o.w = cvtpk(s[6 * 33], s[7 * 33]);
;         bf16* dst = WT + (size_t)(dst_row0 + n0 + n) * dst_pitch + dst_k0 + k0 + 8 * c;
;         for (int cp = 0; cp < ncopies; ++cp) *(u32x4*)(dst + (size_t)cp * copy_stride) = o; }
;     asm volatile("s_waitcnt lgkmcnt(0)" ::: "memory");
.LBB0_204:
	v_add_u32_e32 v30, s4, v19
	v_add_u32_e32 v31, 6, v30
	v_add_u32_e32 v32, 8, v30
	v_add_u32_e32 v34, 10, v30
	v_add_u32_e32 v50, 12, v30
	v_add_u32_e32 v52, 14, v30
	v_mad_i64_i32 v[30:31], s[52:53], v31, s50, v[20:21]
	v_mad_i64_i32 v[32:33], s[52:53], v32, s50, v[20:21]
	v_mad_i64_i32 v[34:35], s[52:53], v34, s50, v[20:21]
	global_load_dword v29, v[26:27], off nt
	global_load_dword v49, v[24:25], off nt
	global_load_dword v54, v[22:23], off nt
	v_mad_i64_i32 v[50:51], s[52:53], v50, s50, v[20:21]
	v_mad_i64_i32 v[52:53], s[52:53], v52, s50, v[20:21]
	global_load_dword v30, v[30:31], off nt
	s_nop 0
	global_load_dword v31, v[32:33], off nt
	s_nop 0
	global_load_dword v32, v[34:35], off nt
	global_load_dword v33, v[50:51], off nt
	s_nop 0
	global_load_dword v34, v[52:53], off nt
	s_add_i32 s4, s4, 16
	v_add_u32_e32 v35, 0x400, v28
	v_lshl_add_u64 v[22:23], v[22:23], 0, s[10:11]
	v_lshl_add_u64 v[24:25], v[24:25], 0, s[10:11]
	v_lshl_add_u64 v[26:27], v[26:27], 0, s[10:11]
	s_cmp_lg_u32 s4, 64
	s_waitcnt vmcnt(0)
	ds_write2_b32 v28, v29, v49 offset1:66
	ds_write2_b32 v28, v54, v30 offset0:132 offset1:198
	ds_write2_b32 v35, v31, v32 offset0:8 offset1:74
	ds_write2_b32 v35, v33, v34 offset0:140 offset1:206
	v_add_u32_e32 v28, 0x840, v28
	s_cbranch_scc1 .LBB0_204
	s_waitcnt lgkmcnt(0)
	ds_read2_b32 v[24:25], v37 offset0:33 offset1:41
	ds_read2_b32 v[26:27], v37 offset1:8
	ds_read2_b32 v[28:29], v37 offset0:66 offset1:74
	ds_read2_b32 v[30:31], v37 offset0:99 offset1:107
	ds_read2_b32 v[32:33], v37 offset0:132 offset1:140
	ds_read2_b32 v[34:35], v37 offset0:165 offset1:173
	ds_read2_b32 v[50:51], v37 offset0:198 offset1:206
	ds_read2_b32 v[52:53], v37 offset0:231 offset1:239
	v_add_u32_e32 v56, s20, v36
	v_ashrrev_i32_e32 v57, 31, v56
	v_lshl_add_u64 v[54:55], s[22:23], 1, v[14:15]
	v_lshlrev_b64 v[56:57], 11, v[56:57]
	s_waitcnt lgkmcnt(6)
	v_cvt_pk_bf16_f32 v20, v26, v24
	s_waitcnt lgkmcnt(4)
	v_cvt_pk_bf16_f32 v21, v28, v30
	s_waitcnt lgkmcnt(2)
	v_cvt_pk_bf16_f32 v22, v32, v34
	s_waitcnt lgkmcnt(0)
	v_cvt_pk_bf16_f32 v23, v50, v52
	v_lshl_add_u64 v[56:57], v[54:55], 0, v[56:57]
	v_add_u32_e32 v24, s20, v38
	global_store_dwordx4 v[56:57], v[20:23], off nt
	s_nop 1
	v_cvt_pk_bf16_f32 v20, v27, v25
	v_ashrrev_i32_e32 v25, 31, v24
	v_cvt_pk_bf16_f32 v21, v29, v31
	v_cvt_pk_bf16_f32 v22, v33, v35
	v_cvt_pk_bf16_f32 v23, v51, v53
	v_lshlrev_b64 v[24:25], 11, v[24:25]
	ds_read2_b32 v[26:27], v37 offset0:49 offset1:57
	ds_read2_b32 v[28:29], v37 offset0:16 offset1:24
	ds_read2_b32 v[30:31], v37 offset0:82 offset1:90
	ds_read2_b32 v[32:33], v37 offset0:115 offset1:123
	ds_read2_b32 v[34:35], v37 offset0:148 offset1:156
	ds_read2_b32 v[50:51], v37 offset0:181 offset1:189
	ds_read2_b32 v[52:53], v37 offset0:214 offset1:222
	ds_read2_b32 v[56:57], v37 offset0:247 offset1:255
	v_lshl_add_u64 v[24:25], v[54:55], 0, v[24:25]
	global_store_dwordx4 v[24:25], v[20:23], off nt
	v_add_u32_e32 v24, s20, v39
	v_ashrrev_i32_e32 v25, 31, v24
	v_lshlrev_b64 v[24:25], 11, v[24:25]
	s_waitcnt lgkmcnt(6)
	v_cvt_pk_bf16_f32 v20, v28, v26
	s_waitcnt lgkmcnt(4)
	v_cvt_pk_bf16_f32 v21, v30, v32
	s_waitcnt lgkmcnt(2)
	v_cvt_pk_bf16_f32 v22, v34, v50
	s_waitcnt lgkmcnt(0)
	v_cvt_pk_bf16_f32 v23, v52, v56
	v_lshl_add_u64 v[24:25], v[54:55], 0, v[24:25]
	global_store_dwordx4 v[24:25], v[20:23], off nt
	v_add_u32_e32 v24, s20, v40
	v_ashrrev_i32_e32 v25, 31, v24
	v_lshlrev_b64 v[24:25], 11, v[24:25]
	v_cvt_pk_bf16_f32 v20, v29, v27
	v_cvt_pk_bf16_f32 v21, v31, v33
	v_cvt_pk_bf16_f32 v22, v35, v51
	v_cvt_pk_bf16_f32 v23, v53, v57
	v_lshl_add_u64 v[24:25], v[54:55], 0, v[24:25]
	global_store_dwordx4 v[24:25], v[20:23], off nt
	s_waitcnt lgkmcnt(0)
	s_branch .LBB0_185
